# rowpass loops: post-ladder vmcnt store drains replaced by s_nop (store-data WAR only), on top of own phase-0 GEMV/converter and blocked 256x128 GEMMs
# speedup vs baseline: 1.0830x; 1.0001x over previous
.LBB0_52:
	s_add_i32 s20, s6, 1
	s_cmp_lt_i32 s20, s36
	s_cselect_b64 s[34:35], -1, 0
	s_cmp_ge_i32 s20, s36
	s_cbranch_scc1 .LBB0_55
	s_ashr_i32 s21, s20, 31
	s_lshl_b64 s[26:27], s[20:21], 12
	s_nop 1
	v_lshl_add_u64 v[46:47], v[122:123], 0, s[26:27]
	global_load_dwordx4 v[34:37], v[46:47], off nt
	global_load_dwordx4 v[38:41], v[46:47], off offset:1024 nt
	global_load_dwordx4 v[42:45], v[46:47], off offset:2048 nt
	s_nop 0
	global_load_dwordx4 v[46:49], v[46:47], off offset:3072 nt
	s_and_b64 vcc, exec, s[38:39]
	s_cbranch_vccnz .LBB0_55
	s_lshl_b64 s[26:27], s[20:21], 11
	v_lshl_add_u64 v[134:135], v[124:125], 0, s[26:27]
	global_load_dwordx2 v[140:141], v[134:135], off nt
	global_load_dwordx2 v[138:139], v[134:135], off offset:512 nt
	global_load_dwordx2 v[136:137], v[134:135], off offset:1024 nt
	s_nop 0
	global_load_dwordx2 v[134:135], v[134:135], off offset:1536 nt

.LBB0_57:
	s_and_b64 vcc, exec, s[40:41]
	s_cbranch_vccnz .LBB0_59
	s_nop 1
	v_mov_b32_e32 v152, v59
	v_mov_b32_e32 v153, v63
	v_mov_b32_e32 v150, v58
	v_mov_b32_e32 v151, v62
	v_pk_mul_f32 v[152:153], v[152:153], v[152:153]
	s_nop 1
	v_mov_b32_e32 v168, v51
	v_pk_fma_f32 v[150:151], v[150:151], v[150:151], v[152:153]
	v_mov_b32_e32 v152, v60
	v_mov_b32_e32 v153, v64
	v_pk_fma_f32 v[150:151], v[152:153], v[152:153], v[150:151]
	v_mov_b32_e32 v152, v61
	v_mov_b32_e32 v153, v65
	v_mov_b32_e32 v169, v55
	v_pk_fma_f32 v[150:151], v[152:153], v[152:153], v[150:151]
	v_mov_b32_e32 v152, v50
	v_mov_b32_e32 v153, v54
	v_pk_mul_f32 v[168:169], v[168:169], v[168:169]
	v_and_b32_e32 v99, 64, v159
	v_pk_fma_f32 v[152:153], v[152:153], v[152:153], v[168:169]
	v_mov_b32_e32 v168, v52
	v_mov_b32_e32 v169, v56
	v_pk_fma_f32 v[152:153], v[168:169], v[168:169], v[152:153]
	v_mov_b32_e32 v168, v53
	v_mov_b32_e32 v169, v57
	v_add_u32_e32 v99, 64, v99
	v_xor_b32_e32 v101, 32, v159
	v_pk_fma_f32 v[152:153], v[168:169], v[168:169], v[152:153]
	v_add_f32_e32 v0, v150, v151
	v_cmp_lt_i32_e32 vcc, v101, v99
	v_add_f32_e32 v0, v153, v0
	v_add_f32_e32 v0, v152, v0
	v_cndmask_b32_e32 v101, v159, v101, vcc
	v_lshlrev_b32_e32 v101, 2, v101
	ds_bpermute_b32 v101, v101, v0
	s_waitcnt lgkmcnt(0)
	v_add_f32_e32 v0, v0, v101
	v_xor_b32_e32 v101, 16, v159
	v_cmp_lt_i32_e32 vcc, v101, v99
	s_nop 1
	v_cndmask_b32_e32 v101, v159, v101, vcc
	v_lshlrev_b32_e32 v101, 2, v101
	ds_bpermute_b32 v101, v101, v0
	s_waitcnt lgkmcnt(0)
	v_add_f32_e32 v0, v0, v101
	v_xor_b32_e32 v101, 8, v159
	v_cmp_lt_i32_e32 vcc, v101, v99
	s_nop 1
	v_cndmask_b32_e32 v101, v159, v101, vcc
	v_lshlrev_b32_e32 v101, 2, v101
	ds_bpermute_b32 v101, v101, v0
	s_waitcnt lgkmcnt(0)
	v_add_f32_e32 v0, v0, v101
	v_xor_b32_e32 v101, 4, v159
	v_cmp_lt_i32_e32 vcc, v101, v99
	s_nop 1
	v_cndmask_b32_e32 v101, v159, v101, vcc
	v_lshlrev_b32_e32 v101, 2, v101
	ds_bpermute_b32 v101, v101, v0
	s_waitcnt lgkmcnt(0)
	v_add_f32_e32 v0, v0, v101
	v_xor_b32_e32 v101, 2, v159
	v_cmp_lt_i32_e32 vcc, v101, v99
	s_nop 1
	v_cndmask_b32_e32 v101, v159, v101, vcc
	v_lshlrev_b32_e32 v101, 2, v101
	ds_bpermute_b32 v101, v101, v0
	s_waitcnt lgkmcnt(0)
	v_add_f32_e32 v0, v0, v101
	v_xor_b32_e32 v101, 1, v159
	v_cmp_lt_i32_e32 vcc, v101, v99
	s_nop 1
	v_cndmask_b32_e32 v99, v159, v101, vcc
	v_lshlrev_b32_e32 v99, 2, v99
	ds_bpermute_b32 v99, v99, v0
	s_waitcnt lgkmcnt(0)
	v_add_f32_e32 v0, v0, v99
	v_fmamk_f32 v0, v0, 0x3a800000, v155
	v_mul_f32_e32 v99, 0x4b800000, v0
	v_cmp_gt_f32_e32 vcc, s84, v0
	s_nop 1
	v_cndmask_b32_e32 v0, v0, v99, vcc
	v_rsq_f32_e32 v0, v0
	s_nop 0
	v_mul_f32_e32 v99, 0x45800000, v0
	v_cndmask_b32_e32 v0, v0, v99, vcc
	v_pk_mul_f32 v[64:65], v[64:65], v[0:1] op_sel_hi:[1,0]
	v_pk_mul_f32 v[62:63], v[62:63], v[0:1] op_sel_hi:[1,0]
	v_pk_mul_f32 v[60:61], v[60:61], v[0:1] op_sel_hi:[1,0]
	v_pk_mul_f32 v[58:59], v[58:59], v[0:1] op_sel_hi:[1,0]
	v_pk_mul_f32 v[56:57], v[56:57], v[0:1] op_sel_hi:[1,0]
	v_pk_mul_f32 v[54:55], v[54:55], v[0:1] op_sel_hi:[1,0]
	v_pk_mul_f32 v[52:53], v[52:53], v[0:1] op_sel_hi:[1,0]
	v_pk_mul_f32 v[50:51], v[50:51], v[0:1] op_sel_hi:[1,0]
	v_pk_mul_f32 v[62:63], v[6:7], v[62:63]
	v_pk_mul_f32 v[64:65], v[8:9], v[64:65]
	v_pk_mul_f32 v[58:59], v[14:15], v[58:59]
	v_pk_mul_f32 v[60:61], v[16:17], v[60:61]
	v_pk_mul_f32 v[54:55], v[22:23], v[54:55]
	v_pk_mul_f32 v[56:57], v[24:25], v[56:57]
	v_pk_mul_f32 v[50:51], v[30:31], v[50:51]
	v_pk_mul_f32 v[52:53], v[32:33], v[52:53]
	v_pk_fma_f32 v[64:65], v[72:73], v[64:65], v[76:77]
	v_pk_fma_f32 v[62:63], v[70:71], v[62:63], v[74:75]
	v_pk_fma_f32 v[60:61], v[84:85], v[60:61], v[88:89]
	v_pk_fma_f32 v[58:59], v[82:83], v[58:59], v[86:87]
	v_pk_fma_f32 v[56:57], v[96:97], v[56:57], v[108:109]
	v_pk_fma_f32 v[54:55], v[94:95], v[54:55], v[106:107]
	v_pk_fma_f32 v[52:53], v[116:117], v[52:53], v[120:121]
	v_pk_fma_f32 v[50:51], v[114:115], v[50:51], v[118:119]
	v_cvt_pk_bf16_f32 v62, v62, v63
	v_cvt_pk_bf16_f32 v63, v64, v65
	v_cvt_pk_bf16_f32 v58, v58, v59
	v_cvt_pk_bf16_f32 v59, v60, v61
	v_cvt_pk_bf16_f32 v54, v54, v55
	v_cvt_pk_bf16_f32 v55, v56, v57
	v_cvt_pk_bf16_f32 v50, v50, v51
	v_cvt_pk_bf16_f32 v51, v52, v53
	v_readlane_b32 vcc_lo, v244, 60
	v_readlane_b32 vcc_hi, v244, 61
	s_nop 3
	v_subrev_u32_e32 v64, vcc_lo, v132
	v_add_u32_e32 v64, 0xfffffc00, v64
	v_and_b32_e32 v60, 0x7ff, v64
	v_lshrrev_b32_e32 v64, 11, v64
	v_lshlrev_b32_e32 v64, 6, v64
	v_lshrrev_b32_e32 v61, 6, v60
	v_lshl_or_b32 v64, v61, 20, v64
	v_and_or_b32 v64, v60, 63, v64
	v_mov_b32_e32 v65, 0
	v_lshl_add_u64 v[64:65], vcc, 0, v[64:65]
	global_store_dwordx2 v[64:65], v[62:63], off
	v_subrev_u32_e32 v64, vcc_lo, v132
	v_add_u32_e32 v64, 0xfffffe00, v64
	v_and_b32_e32 v60, 0x7ff, v64
	v_lshrrev_b32_e32 v64, 11, v64
	v_lshlrev_b32_e32 v64, 6, v64
	v_lshrrev_b32_e32 v61, 6, v60
	v_lshl_or_b32 v64, v61, 20, v64
	v_and_or_b32 v64, v60, 63, v64
	v_mov_b32_e32 v65, 0
	v_lshl_add_u64 v[64:65], vcc, 0, v[64:65]
	global_store_dwordx2 v[64:65], v[58:59], off
	v_subrev_u32_e32 v64, vcc_lo, v132
	v_and_b32_e32 v60, 0x7ff, v64
	v_lshrrev_b32_e32 v64, 11, v64
	v_lshlrev_b32_e32 v64, 6, v64
	v_lshrrev_b32_e32 v61, 6, v60
	v_lshl_or_b32 v64, v61, 20, v64
	v_and_or_b32 v64, v60, 63, v64
	v_mov_b32_e32 v65, 0
	v_lshl_add_u64 v[64:65], vcc, 0, v[64:65]
	global_store_dwordx2 v[64:65], v[54:55], off
	v_subrev_u32_e32 v64, vcc_lo, v132
	v_add_u32_e32 v64, 0x200, v64
	v_and_b32_e32 v60, 0x7ff, v64
	v_lshrrev_b32_e32 v64, 11, v64
	v_lshlrev_b32_e32 v64, 6, v64
	v_lshrrev_b32_e32 v61, 6, v60
	v_lshl_or_b32 v64, v61, 20, v64
	v_and_or_b32 v64, v60, 63, v64
	v_mov_b32_e32 v65, 0
	v_lshl_add_u64 v[64:65], vcc, 0, v[64:65]
	global_store_dwordx2 v[64:65], v[50:51], off
.LBB0_59:
	s_andn2_b64 vcc, exec, s[34:35]
	s_cbranch_vccnz .LBB0_49
	s_and_b64 vcc, exec, s[38:39]
	s_cbranch_vccnz .LBB0_62
	s_nop 1
	v_and_b32_e32 v53, 0xffff0000, v140
	v_and_b32_e32 v52, 0xffff0000, v138
	v_lshlrev_b32_e32 v51, 16, v140
	v_lshlrev_b32_e32 v50, 16, v138
	v_pk_mul_f32 v[58:59], v[52:53], v[52:53]
	v_lshlrev_b32_e32 v55, 16, v141
	v_lshlrev_b32_e32 v54, 16, v139
	v_pk_fma_f32 v[58:59], v[50:51], v[50:51], v[58:59]
	v_and_b32_e32 v57, 0xffff0000, v141
	v_and_b32_e32 v56, 0xffff0000, v139
	v_pk_fma_f32 v[58:59], v[54:55], v[54:55], v[58:59]
	v_and_b32_e32 v63, 0xffff0000, v136
	v_and_b32_e32 v62, 0xffff0000, v134
	v_pk_fma_f32 v[58:59], v[56:57], v[56:57], v[58:59]
	v_lshlrev_b32_e32 v61, 16, v136
	v_lshlrev_b32_e32 v60, 16, v134
	v_pk_mul_f32 v[152:153], v[62:63], v[62:63]
	v_lshlrev_b32_e32 v65, 16, v137
	v_lshlrev_b32_e32 v64, 16, v135
	v_pk_fma_f32 v[152:153], v[60:61], v[60:61], v[152:153]
	v_add_f32_e32 v0, v58, v59
	v_and_b32_e32 v58, 64, v159
	v_and_b32_e32 v151, 0xffff0000, v137
	v_and_b32_e32 v150, 0xffff0000, v135
	v_pk_fma_f32 v[152:153], v[64:65], v[64:65], v[152:153]
	v_add_u32_e32 v58, 64, v58
	v_xor_b32_e32 v59, 32, v159
	v_pk_fma_f32 v[152:153], v[150:151], v[150:151], v[152:153]
	v_cmp_lt_i32_e32 vcc, v59, v58
	v_add_f32_e32 v0, v153, v0
	v_add_f32_e32 v0, v152, v0
	v_cndmask_b32_e32 v59, v159, v59, vcc
	v_lshlrev_b32_e32 v59, 2, v59
	ds_bpermute_b32 v59, v59, v0
	v_mov_b32_e32 v152, v55
	v_mov_b32_e32 v168, v51
	v_mov_b32_e32 v55, v56
	v_mov_b32_e32 v51, v52
	s_waitcnt lgkmcnt(0)
	v_add_f32_e32 v0, v0, v59
	v_xor_b32_e32 v59, 16, v159
	v_cmp_lt_i32_e32 vcc, v59, v58
	v_mov_b32_e32 v169, v53
	v_mov_b32_e32 v153, v57
	v_cndmask_b32_e32 v59, v159, v59, vcc
	v_lshlrev_b32_e32 v59, 2, v59
	ds_bpermute_b32 v59, v59, v0
	s_ashr_i32 s21, s20, 31
	s_lshl_b64 s[26:27], s[20:21], 12
	s_waitcnt lgkmcnt(0)
	v_add_f32_e32 v0, v0, v59
	v_xor_b32_e32 v59, 8, v159
	v_cmp_lt_i32_e32 vcc, v59, v58
	s_nop 1
	v_cndmask_b32_e32 v59, v159, v59, vcc
	v_lshlrev_b32_e32 v59, 2, v59
	ds_bpermute_b32 v59, v59, v0
	s_waitcnt lgkmcnt(0)
	v_add_f32_e32 v0, v0, v59
	v_xor_b32_e32 v59, 4, v159
	v_cmp_lt_i32_e32 vcc, v59, v58
	s_nop 1
	v_cndmask_b32_e32 v59, v159, v59, vcc
	v_lshlrev_b32_e32 v59, 2, v59
	ds_bpermute_b32 v59, v59, v0
	s_waitcnt lgkmcnt(0)
	v_add_f32_e32 v0, v0, v59
	v_xor_b32_e32 v59, 2, v159
	v_cmp_lt_i32_e32 vcc, v59, v58
	s_nop 1
	v_cndmask_b32_e32 v59, v159, v59, vcc
	v_lshlrev_b32_e32 v59, 2, v59
	ds_bpermute_b32 v59, v59, v0
	s_waitcnt lgkmcnt(0)
	v_add_f32_e32 v0, v0, v59
	v_xor_b32_e32 v59, 1, v159
	v_cmp_lt_i32_e32 vcc, v59, v58
	s_nop 1
	v_cndmask_b32_e32 v58, v159, v59, vcc
	v_lshlrev_b32_e32 v58, 2, v58
	ds_bpermute_b32 v58, v58, v0
	s_waitcnt lgkmcnt(0)
	v_add_f32_e32 v0, v0, v58
	v_fmamk_f32 v0, v0, 0x3a800000, v155
	v_mul_f32_e32 v58, 0x4b800000, v0
	v_cmp_gt_f32_e32 vcc, s84, v0
	s_nop 1
	v_cndmask_b32_e32 v0, v0, v58, vcc
	v_rsq_f32_e32 v0, v0
	s_nop 0
	v_mul_f32_e32 v58, 0x45800000, v0
	v_cndmask_b32_e32 v0, v0, v58, vcc
	v_pk_mul_f32 v[54:55], v[54:55], v[0:1] op_sel_hi:[1,0]
	v_pk_mul_f32 v[50:51], v[50:51], v[0:1] op_sel_hi:[1,0]
	v_pk_mul_f32 v[52:53], v[80:81], v[54:55]
	v_pk_mul_f32 v[50:51], v[78:79], v[50:51]
	v_pk_fma_f32 v[40:41], v[12:13], v[52:53], v[40:41]
	v_pk_fma_f32 v[38:39], v[10:11], v[50:51], v[38:39]
	v_mov_b32_e32 v50, v65
	v_mov_b32_e32 v51, v151
	v_mov_b32_e32 v52, v61
	v_mov_b32_e32 v53, v63
	v_pk_mul_f32 v[50:51], v[50:51], v[0:1] op_sel_hi:[1,0]
	v_pk_mul_f32 v[52:53], v[52:53], v[0:1] op_sel_hi:[1,0]
	v_pk_mul_f32 v[50:51], v[92:93], v[50:51]
	v_pk_mul_f32 v[52:53], v[90:91], v[52:53]
	v_mov_b32_e32 v65, v150
	v_mov_b32_e32 v61, v62
	v_pk_mul_f32 v[152:153], v[152:153], v[0:1] op_sel_hi:[1,0]
	v_pk_mul_f32 v[168:169], v[168:169], v[0:1] op_sel_hi:[1,0]
	v_pk_fma_f32 v[44:45], v[20:21], v[50:51], v[44:45]
	v_pk_fma_f32 v[42:43], v[18:19], v[52:53], v[42:43]
	v_pk_mul_f32 v[50:51], v[64:65], v[0:1] op_sel_hi:[1,0]
	v_pk_mul_f32 v[52:53], v[60:61], v[0:1] op_sel_hi:[1,0]
	v_pk_mul_f32 v[168:169], v[66:67], v[168:169]
	v_pk_mul_f32 v[152:153], v[68:69], v[152:153]
	v_pk_mul_f32 v[52:53], v[110:111], v[52:53]
	v_pk_mul_f32 v[50:51], v[112:113], v[50:51]
	v_lshl_add_u64 v[58:59], v[122:123], 0, s[26:27]
	v_pk_fma_f32 v[36:37], v[4:5], v[152:153], v[36:37]
	v_pk_fma_f32 v[34:35], v[2:3], v[168:169], v[34:35]
	v_pk_fma_f32 v[48:49], v[28:29], v[50:51], v[48:49]
	v_pk_fma_f32 v[46:47], v[26:27], v[52:53], v[46:47]
	global_store_dwordx4 v[58:59], v[34:37], off nt
	global_store_dwordx4 v[58:59], v[38:41], off offset:1024 nt
	global_store_dwordx4 v[58:59], v[42:45], off offset:2048 nt
	global_store_dwordx4 v[58:59], v[46:49], off offset:3072 nt
.LBB0_62:
	s_and_b64 vcc, exec, s[40:41]
	s_cbranch_vccnz .LBB0_49
	s_nop 1
	v_mov_b32_e32 v52, v39
	v_mov_b32_e32 v53, v35
	v_mov_b32_e32 v50, v38
	v_mov_b32_e32 v51, v34
	v_pk_mul_f32 v[52:53], v[52:53], v[52:53]
	v_mov_b32_e32 v54, v47
	v_pk_fma_f32 v[50:51], v[50:51], v[50:51], v[52:53]
	v_mov_b32_e32 v52, v40
	v_mov_b32_e32 v53, v36
	v_pk_fma_f32 v[50:51], v[52:53], v[52:53], v[50:51]
	v_mov_b32_e32 v52, v41
	v_mov_b32_e32 v53, v37
	v_mov_b32_e32 v55, v43
	v_pk_fma_f32 v[50:51], v[52:53], v[52:53], v[50:51]
	v_mov_b32_e32 v52, v46
	v_mov_b32_e32 v53, v42
	v_pk_mul_f32 v[54:55], v[54:55], v[54:55]
	v_add_f32_e32 v0, v50, v51
	v_pk_fma_f32 v[52:53], v[52:53], v[52:53], v[54:55]
	v_mov_b32_e32 v54, v48
	v_mov_b32_e32 v55, v44
	v_and_b32_e32 v50, 64, v159
	v_pk_fma_f32 v[52:53], v[54:55], v[54:55], v[52:53]
	v_mov_b32_e32 v54, v49
	v_mov_b32_e32 v55, v45
	v_add_u32_e32 v50, 64, v50
	v_xor_b32_e32 v51, 32, v159
	v_pk_fma_f32 v[52:53], v[54:55], v[54:55], v[52:53]
	v_cmp_lt_i32_e32 vcc, v51, v50
	v_add_f32_e32 v0, v53, v0
	v_add_f32_e32 v0, v52, v0
	v_cndmask_b32_e32 v51, v159, v51, vcc
	v_lshlrev_b32_e32 v51, 2, v51
	ds_bpermute_b32 v51, v51, v0
	s_ashr_i32 s21, s20, 31
	s_lshl_b64 s[20:21], s[20:21], 11
	s_waitcnt lgkmcnt(0)
	v_add_f32_e32 v0, v0, v51
	v_xor_b32_e32 v51, 16, v159
	v_cmp_lt_i32_e32 vcc, v51, v50
	s_nop 1
	v_cndmask_b32_e32 v51, v159, v51, vcc
	v_lshlrev_b32_e32 v51, 2, v51
	ds_bpermute_b32 v51, v51, v0
	s_waitcnt lgkmcnt(0)
	v_add_f32_e32 v0, v0, v51
	v_xor_b32_e32 v51, 8, v159
	v_cmp_lt_i32_e32 vcc, v51, v50
	s_nop 1
	v_cndmask_b32_e32 v51, v159, v51, vcc
	v_lshlrev_b32_e32 v51, 2, v51
	ds_bpermute_b32 v51, v51, v0
	s_waitcnt lgkmcnt(0)
	v_add_f32_e32 v0, v0, v51
	v_xor_b32_e32 v51, 4, v159
	v_cmp_lt_i32_e32 vcc, v51, v50
	s_nop 1
	v_cndmask_b32_e32 v51, v159, v51, vcc
	v_lshlrev_b32_e32 v51, 2, v51
	ds_bpermute_b32 v51, v51, v0
	s_waitcnt lgkmcnt(0)
	v_add_f32_e32 v0, v0, v51
	v_xor_b32_e32 v51, 2, v159
	v_cmp_lt_i32_e32 vcc, v51, v50
	s_nop 1
	v_cndmask_b32_e32 v51, v159, v51, vcc
	v_lshlrev_b32_e32 v51, 2, v51
	ds_bpermute_b32 v51, v51, v0
	s_waitcnt lgkmcnt(0)
	v_add_f32_e32 v0, v0, v51
	v_xor_b32_e32 v51, 1, v159
	v_cmp_lt_i32_e32 vcc, v51, v50
	s_nop 1
	v_cndmask_b32_e32 v50, v159, v51, vcc
	v_lshlrev_b32_e32 v50, 2, v50
	ds_bpermute_b32 v50, v50, v0
	s_waitcnt lgkmcnt(0)
	v_add_f32_e32 v0, v0, v50
	v_fmamk_f32 v0, v0, 0x3a800000, v155
	v_mul_f32_e32 v50, 0x4b800000, v0
	v_cmp_gt_f32_e32 vcc, s84, v0
	s_nop 1
	v_cndmask_b32_e32 v0, v0, v50, vcc
	v_rsq_f32_e32 v0, v0
	s_nop 0
	v_mul_f32_e32 v50, 0x45800000, v0
	v_cndmask_b32_e32 v0, v0, v50, vcc
	v_pk_mul_f32 v[52:53], v[36:37], v[0:1] op_sel_hi:[1,0]
	v_pk_mul_f32 v[54:55], v[34:35], v[0:1] op_sel_hi:[1,0]
	v_pk_mul_f32 v[52:53], v[8:9], v[52:53]
	v_pk_mul_f32 v[54:55], v[6:7], v[54:55]
	v_pk_fma_f32 v[52:53], v[72:73], v[52:53], v[76:77]
	v_pk_fma_f32 v[54:55], v[70:71], v[54:55], v[74:75]
	v_lshl_add_u64 v[50:51], v[126:127], 0, s[20:21]
	v_cvt_pk_bf16_f32 v54, v54, v55
	v_cvt_pk_bf16_f32 v55, v52, v53
	v_readlane_b32 vcc_lo, v244, 60
	v_readlane_b32 vcc_hi, v244, 61
	s_nop 3
	v_subrev_u32_e32 v34, vcc_lo, v50
	v_and_b32_e32 v36, 0x7ff, v34
	v_lshrrev_b32_e32 v34, 11, v34
	v_lshlrev_b32_e32 v34, 6, v34
	v_lshrrev_b32_e32 v37, 6, v36
	v_lshl_or_b32 v34, v37, 20, v34
	v_and_or_b32 v34, v36, 63, v34
	v_mov_b32_e32 v35, 0
	v_lshl_add_u64 v[34:35], vcc, 0, v[34:35]
	global_store_dwordx2 v[34:35], v[54:55], off
	v_pk_mul_f32 v[52:53], v[40:41], v[0:1] op_sel_hi:[1,0]
	v_pk_mul_f32 v[54:55], v[38:39], v[0:1] op_sel_hi:[1,0]
	v_pk_mul_f32 v[52:53], v[16:17], v[52:53]
	v_pk_mul_f32 v[54:55], v[14:15], v[54:55]
	v_pk_fma_f32 v[52:53], v[84:85], v[52:53], v[88:89]
	v_pk_fma_f32 v[54:55], v[82:83], v[54:55], v[86:87]
	s_nop 0
	v_cvt_pk_bf16_f32 v54, v54, v55
	v_cvt_pk_bf16_f32 v55, v52, v53
	v_subrev_u32_e32 v34, vcc_lo, v50
	v_add_u32_e32 v34, 0x200, v34
	v_and_b32_e32 v36, 0x7ff, v34
	v_lshrrev_b32_e32 v34, 11, v34
	v_lshlrev_b32_e32 v34, 6, v34
	v_lshrrev_b32_e32 v37, 6, v36
	v_lshl_or_b32 v34, v37, 20, v34
	v_and_or_b32 v34, v36, 63, v34
	v_mov_b32_e32 v35, 0
	v_lshl_add_u64 v[34:35], vcc, 0, v[34:35]
	global_store_dwordx2 v[34:35], v[54:55], off
	v_pk_mul_f32 v[52:53], v[44:45], v[0:1] op_sel_hi:[1,0]
	v_pk_mul_f32 v[54:55], v[42:43], v[0:1] op_sel_hi:[1,0]
	v_pk_mul_f32 v[52:53], v[24:25], v[52:53]
	v_pk_mul_f32 v[54:55], v[22:23], v[54:55]
	v_pk_fma_f32 v[52:53], v[96:97], v[52:53], v[108:109]
	v_pk_fma_f32 v[54:55], v[94:95], v[54:55], v[106:107]
	s_nop 0
	v_cvt_pk_bf16_f32 v54, v54, v55
	v_cvt_pk_bf16_f32 v55, v52, v53
	v_subrev_u32_e32 v34, vcc_lo, v50
	v_add_u32_e32 v34, 0x400, v34
	v_and_b32_e32 v36, 0x7ff, v34
	v_lshrrev_b32_e32 v34, 11, v34
	v_lshlrev_b32_e32 v34, 6, v34
	v_lshrrev_b32_e32 v37, 6, v36
	v_lshl_or_b32 v34, v37, 20, v34
	v_and_or_b32 v34, v36, 63, v34
	v_mov_b32_e32 v35, 0
	v_lshl_add_u64 v[34:35], vcc, 0, v[34:35]
	global_store_dwordx2 v[34:35], v[54:55], off
	v_pk_mul_f32 v[52:53], v[48:49], v[0:1] op_sel_hi:[1,0]
	v_pk_mul_f32 v[54:55], v[46:47], v[0:1] op_sel_hi:[1,0]
	v_pk_mul_f32 v[52:53], v[32:33], v[52:53]
	v_pk_mul_f32 v[54:55], v[30:31], v[54:55]
	v_pk_fma_f32 v[52:53], v[116:117], v[52:53], v[120:121]
	v_pk_fma_f32 v[54:55], v[114:115], v[54:55], v[118:119]
	s_nop 0
	v_cvt_pk_bf16_f32 v54, v54, v55
	v_cvt_pk_bf16_f32 v55, v52, v53
	v_subrev_u32_e32 v34, vcc_lo, v50
	v_add_u32_e32 v34, 0x600, v34
	v_and_b32_e32 v36, 0x7ff, v34
	v_lshrrev_b32_e32 v34, 11, v34
	v_lshlrev_b32_e32 v34, 6, v34
	v_lshrrev_b32_e32 v37, 6, v36
	v_lshl_or_b32 v34, v37, 20, v34
	v_and_or_b32 v34, v36, 63, v34
	v_mov_b32_e32 v35, 0
	v_lshl_add_u64 v[34:35], vcc, 0, v[34:35]
	global_store_dwordx2 v[34:35], v[54:55], off
	s_branch .LBB0_49

.LBB0_143:
	s_nop 1
	v_lshl_add_u64 v[50:51], s[28:29], 0, v[0:1]
	global_load_dwordx4 v[62:65], v[50:51], off nt
	global_load_dwordx4 v[58:61], v[50:51], off offset:1024 nt
	global_load_dwordx4 v[54:57], v[50:51], off offset:2048 nt
	s_nop 0
	global_load_dwordx4 v[50:53], v[50:51], off offset:3072 nt
	s_and_b64 vcc, exec, s[38:39]
	s_cbranch_vccnz .LBB0_145
	v_lshl_add_u64 v[140:141], s[24:25], 0, v[130:131]
	global_load_dwordx2 v[146:147], v[140:141], off nt
	global_load_dwordx2 v[144:145], v[140:141], off offset:512 nt
	global_load_dwordx2 v[142:143], v[140:141], off offset:1024 nt
	s_nop 0
	global_load_dwordx2 v[140:141], v[140:141], off offset:1536 nt

.LBB0_150:
	s_and_b64 vcc, exec, s[40:41]
	s_cbranch_vccnz .LBB0_152
	s_nop 1
	v_mov_b32_e32 v150, v59
	v_mov_b32_e32 v151, v63
	v_mov_b32_e32 v148, v58
	v_mov_b32_e32 v149, v62
	v_pk_mul_f32 v[150:151], v[150:151], v[150:151]
	s_nop 1
	v_mov_b32_e32 v152, v51
	v_pk_fma_f32 v[148:149], v[148:149], v[148:149], v[150:151]
	v_mov_b32_e32 v150, v60
	v_mov_b32_e32 v151, v64
	v_pk_fma_f32 v[148:149], v[150:151], v[150:151], v[148:149]
	v_mov_b32_e32 v150, v61
	v_mov_b32_e32 v151, v65
	v_mov_b32_e32 v153, v55
	v_pk_fma_f32 v[148:149], v[150:151], v[150:151], v[148:149]
	v_mov_b32_e32 v150, v50
	v_mov_b32_e32 v151, v54
	v_pk_mul_f32 v[152:153], v[152:153], v[152:153]
	v_and_b32_e32 v101, 64, v159
	v_pk_fma_f32 v[150:151], v[150:151], v[150:151], v[152:153]
	v_mov_b32_e32 v152, v52
	v_mov_b32_e32 v153, v56
	v_pk_fma_f32 v[150:151], v[152:153], v[152:153], v[150:151]
	v_mov_b32_e32 v152, v53
	v_mov_b32_e32 v153, v57
	v_add_u32_e32 v101, 64, v101
	v_xor_b32_e32 v103, 32, v159
	v_pk_fma_f32 v[150:151], v[152:153], v[152:153], v[150:151]
	v_add_f32_e32 v99, v148, v149
	v_cmp_lt_i32_e32 vcc, v103, v101
	v_add_f32_e32 v99, v151, v99
	v_add_f32_e32 v99, v150, v99
	v_cndmask_b32_e32 v103, v159, v103, vcc
	v_lshlrev_b32_e32 v103, 2, v103
	ds_bpermute_b32 v103, v103, v99
	v_lshl_add_u64 v[150:151], s[26:27], 0, v[130:131]
	s_waitcnt lgkmcnt(0)
	v_add_f32_e32 v99, v99, v103
	v_xor_b32_e32 v103, 16, v159
	v_cmp_lt_i32_e32 vcc, v103, v101
	s_nop 1
	v_cndmask_b32_e32 v103, v159, v103, vcc
	v_lshlrev_b32_e32 v103, 2, v103
	ds_bpermute_b32 v103, v103, v99
	s_waitcnt lgkmcnt(0)
	v_add_f32_e32 v99, v99, v103
	v_xor_b32_e32 v103, 8, v159
	v_cmp_lt_i32_e32 vcc, v103, v101
	s_nop 1
	v_cndmask_b32_e32 v103, v159, v103, vcc
	v_lshlrev_b32_e32 v103, 2, v103
	ds_bpermute_b32 v103, v103, v99
	s_waitcnt lgkmcnt(0)
	v_add_f32_e32 v99, v99, v103
	v_xor_b32_e32 v103, 4, v159
	v_cmp_lt_i32_e32 vcc, v103, v101
	s_nop 1
	v_cndmask_b32_e32 v103, v159, v103, vcc
	v_lshlrev_b32_e32 v103, 2, v103
	ds_bpermute_b32 v103, v103, v99
	s_waitcnt lgkmcnt(0)
	v_add_f32_e32 v99, v99, v103
	v_xor_b32_e32 v103, 2, v159
	v_cmp_lt_i32_e32 vcc, v103, v101
	s_nop 1
	v_cndmask_b32_e32 v103, v159, v103, vcc
	v_lshlrev_b32_e32 v103, 2, v103
	ds_bpermute_b32 v103, v103, v99
	s_waitcnt lgkmcnt(0)
	v_add_f32_e32 v99, v99, v103
	v_xor_b32_e32 v103, 1, v159
	v_cmp_lt_i32_e32 vcc, v103, v101
	s_nop 1
	v_cndmask_b32_e32 v101, v159, v103, vcc
	v_lshlrev_b32_e32 v101, 2, v101
	ds_bpermute_b32 v101, v101, v99
	s_waitcnt lgkmcnt(0)
	v_add_f32_e32 v99, v99, v101
	v_fmamk_f32 v99, v99, 0x3a800000, v155
	v_mul_f32_e32 v101, 0x4b800000, v99
	v_cmp_gt_f32_e32 vcc, s84, v99
	s_nop 1
	v_cndmask_b32_e32 v99, v99, v101, vcc
	v_rsq_f32_e32 v99, v99
	s_nop 0
	v_mul_f32_e32 v101, 0x45800000, v99
	v_cndmask_b32_e32 v148, v99, v101, vcc
	v_pk_mul_f32 v[64:65], v[64:65], v[148:149] op_sel_hi:[1,0]
	v_pk_mul_f32 v[62:63], v[62:63], v[148:149] op_sel_hi:[1,0]
	v_pk_mul_f32 v[60:61], v[60:61], v[148:149] op_sel_hi:[1,0]
	v_pk_mul_f32 v[58:59], v[58:59], v[148:149] op_sel_hi:[1,0]
	v_pk_mul_f32 v[56:57], v[56:57], v[148:149] op_sel_hi:[1,0]
	v_pk_mul_f32 v[54:55], v[54:55], v[148:149] op_sel_hi:[1,0]
	v_pk_mul_f32 v[52:53], v[52:53], v[148:149] op_sel_hi:[1,0]
	v_pk_mul_f32 v[50:51], v[50:51], v[148:149] op_sel_hi:[1,0]
	v_pk_mul_f32 v[62:63], v[6:7], v[62:63]
	v_pk_mul_f32 v[64:65], v[8:9], v[64:65]
	v_pk_mul_f32 v[58:59], v[14:15], v[58:59]
	v_pk_mul_f32 v[60:61], v[16:17], v[60:61]
	v_pk_mul_f32 v[54:55], v[22:23], v[54:55]
	v_pk_mul_f32 v[56:57], v[24:25], v[56:57]
	v_pk_mul_f32 v[50:51], v[30:31], v[50:51]
	v_pk_mul_f32 v[52:53], v[32:33], v[52:53]
	v_pk_fma_f32 v[64:65], v[72:73], v[64:65], v[76:77]
	v_pk_fma_f32 v[62:63], v[70:71], v[62:63], v[74:75]
	v_pk_fma_f32 v[60:61], v[84:85], v[60:61], v[88:89]
	v_pk_fma_f32 v[58:59], v[82:83], v[58:59], v[86:87]
	v_pk_fma_f32 v[56:57], v[96:97], v[56:57], v[108:109]
	v_pk_fma_f32 v[54:55], v[94:95], v[54:55], v[106:107]
	v_pk_fma_f32 v[52:53], v[116:117], v[52:53], v[120:121]
	v_pk_fma_f32 v[50:51], v[114:115], v[50:51], v[118:119]
	v_cvt_pk_bf16_f32 v62, v62, v63
	v_cvt_pk_bf16_f32 v63, v64, v65
	v_cvt_pk_bf16_f32 v58, v58, v59
	v_cvt_pk_bf16_f32 v59, v60, v61
	v_cvt_pk_bf16_f32 v54, v54, v55
	v_cvt_pk_bf16_f32 v55, v56, v57
	v_cvt_pk_bf16_f32 v50, v50, v51
	v_cvt_pk_bf16_f32 v51, v52, v53
	v_readlane_b32 vcc_lo, v244, 60
	v_readlane_b32 vcc_hi, v244, 61
	s_nop 3
	v_subrev_u32_e32 v64, vcc_lo, v150
	v_and_b32_e32 v60, 0x7ff, v64
	v_lshrrev_b32_e32 v64, 11, v64
	v_lshlrev_b32_e32 v64, 6, v64
	v_lshrrev_b32_e32 v61, 6, v60
	v_lshl_or_b32 v64, v61, 20, v64
	v_and_or_b32 v64, v60, 63, v64
	v_mov_b32_e32 v65, 0
	v_lshl_add_u64 v[64:65], vcc, 0, v[64:65]
	global_store_dwordx2 v[64:65], v[62:63], off
	v_subrev_u32_e32 v64, vcc_lo, v150
	v_add_u32_e32 v64, 0x200, v64
	v_and_b32_e32 v60, 0x7ff, v64
	v_lshrrev_b32_e32 v64, 11, v64
	v_lshlrev_b32_e32 v64, 6, v64
	v_lshrrev_b32_e32 v61, 6, v60
	v_lshl_or_b32 v64, v61, 20, v64
	v_and_or_b32 v64, v60, 63, v64
	v_mov_b32_e32 v65, 0
	v_lshl_add_u64 v[64:65], vcc, 0, v[64:65]
	global_store_dwordx2 v[64:65], v[58:59], off
	v_subrev_u32_e32 v64, vcc_lo, v150
	v_add_u32_e32 v64, 0x400, v64
	v_and_b32_e32 v60, 0x7ff, v64
	v_lshrrev_b32_e32 v64, 11, v64
	v_lshlrev_b32_e32 v64, 6, v64
	v_lshrrev_b32_e32 v61, 6, v60
	v_lshl_or_b32 v64, v61, 20, v64
	v_and_or_b32 v64, v60, 63, v64
	v_mov_b32_e32 v65, 0
	v_lshl_add_u64 v[64:65], vcc, 0, v[64:65]
	global_store_dwordx2 v[64:65], v[54:55], off
	v_subrev_u32_e32 v64, vcc_lo, v150
	v_add_u32_e32 v64, 0x600, v64
	v_and_b32_e32 v60, 0x7ff, v64
	v_lshrrev_b32_e32 v64, 11, v64
	v_lshlrev_b32_e32 v64, 6, v64
	v_lshrrev_b32_e32 v61, 6, v60
	v_lshl_or_b32 v64, v61, 20, v64
	v_and_or_b32 v64, v60, 63, v64
	v_mov_b32_e32 v65, 0
	v_lshl_add_u64 v[64:65], vcc, 0, v[64:65]
	global_store_dwordx2 v[64:65], v[50:51], off
.LBB0_152:
	s_andn2_b64 vcc, exec, s[36:37]
	s_cbranch_vccnz .LBB0_142
	s_and_b64 vcc, exec, s[38:39]
	s_cbranch_vccnz .LBB0_155
	s_nop 1
	v_and_b32_e32 v53, 0xffff0000, v138
	v_and_b32_e32 v52, 0xffff0000, v136
	v_lshlrev_b32_e32 v51, 16, v138
	v_lshlrev_b32_e32 v50, 16, v136
	v_pk_mul_f32 v[58:59], v[52:53], v[52:53]
	v_lshlrev_b32_e32 v55, 16, v139
	v_lshlrev_b32_e32 v54, 16, v137
	v_pk_fma_f32 v[58:59], v[50:51], v[50:51], v[58:59]
	v_and_b32_e32 v57, 0xffff0000, v139
	v_and_b32_e32 v56, 0xffff0000, v137
	v_pk_fma_f32 v[58:59], v[54:55], v[54:55], v[58:59]
	v_and_b32_e32 v63, 0xffff0000, v134
	v_and_b32_e32 v62, 0xffff0000, v132
	v_pk_fma_f32 v[58:59], v[56:57], v[56:57], v[58:59]
	v_lshlrev_b32_e32 v61, 16, v134
	v_lshlrev_b32_e32 v60, 16, v132
	v_pk_mul_f32 v[150:151], v[62:63], v[62:63]
	v_lshlrev_b32_e32 v65, 16, v135
	v_lshlrev_b32_e32 v64, 16, v133
	v_pk_fma_f32 v[150:151], v[60:61], v[60:61], v[150:151]
	v_add_f32_e32 v58, v58, v59
	v_and_b32_e32 v59, 64, v159
	v_and_b32_e32 v149, 0xffff0000, v135
	v_and_b32_e32 v148, 0xffff0000, v133
	v_pk_fma_f32 v[150:151], v[64:65], v[64:65], v[150:151]
	v_add_u32_e32 v59, 64, v59
	v_xor_b32_e32 v99, 32, v159
	v_pk_fma_f32 v[150:151], v[148:149], v[148:149], v[150:151]
	v_cmp_lt_i32_e32 vcc, v99, v59
	v_add_f32_e32 v58, v151, v58
	v_add_f32_e32 v58, v150, v58
	v_cndmask_b32_e32 v99, v159, v99, vcc
	v_lshlrev_b32_e32 v99, 2, v99
	ds_bpermute_b32 v99, v99, v58
	v_mov_b32_e32 v152, v55
	v_mov_b32_e32 v168, v51
	v_mov_b32_e32 v55, v56
	v_mov_b32_e32 v51, v52
	s_waitcnt lgkmcnt(0)
	v_add_f32_e32 v58, v58, v99
	v_xor_b32_e32 v99, 16, v159
	v_cmp_lt_i32_e32 vcc, v99, v59
	v_mov_b32_e32 v169, v53
	v_mov_b32_e32 v153, v57
	v_cndmask_b32_e32 v99, v159, v99, vcc
	v_lshlrev_b32_e32 v99, 2, v99
	ds_bpermute_b32 v99, v99, v58
	s_ashr_i32 s35, s34, 31
	s_lshl_b64 s[20:21], s[34:35], 12
	v_lshl_add_u64 v[150:151], v[126:127], 0, s[20:21]
	s_waitcnt lgkmcnt(0)
	v_add_f32_e32 v58, v58, v99
	v_xor_b32_e32 v99, 8, v159
	v_cmp_lt_i32_e32 vcc, v99, v59
	s_nop 1
	v_cndmask_b32_e32 v99, v159, v99, vcc
	v_lshlrev_b32_e32 v99, 2, v99
	ds_bpermute_b32 v99, v99, v58
	s_waitcnt lgkmcnt(0)
	v_add_f32_e32 v58, v58, v99
	v_xor_b32_e32 v99, 4, v159
	v_cmp_lt_i32_e32 vcc, v99, v59
	s_nop 1
	v_cndmask_b32_e32 v99, v159, v99, vcc
	v_lshlrev_b32_e32 v99, 2, v99
	ds_bpermute_b32 v99, v99, v58
	s_waitcnt lgkmcnt(0)
	v_add_f32_e32 v58, v58, v99
	v_xor_b32_e32 v99, 2, v159
	v_cmp_lt_i32_e32 vcc, v99, v59
	s_nop 1
	v_cndmask_b32_e32 v99, v159, v99, vcc
	v_lshlrev_b32_e32 v99, 2, v99
	ds_bpermute_b32 v99, v99, v58
	s_waitcnt lgkmcnt(0)
	v_add_f32_e32 v58, v58, v99
	v_xor_b32_e32 v99, 1, v159
	v_cmp_lt_i32_e32 vcc, v99, v59
	s_nop 1
	v_cndmask_b32_e32 v59, v159, v99, vcc
	v_lshlrev_b32_e32 v59, 2, v59
	ds_bpermute_b32 v59, v59, v58
	s_waitcnt lgkmcnt(0)
	v_add_f32_e32 v58, v58, v59
	v_fmamk_f32 v58, v58, 0x3a800000, v155
	v_mul_f32_e32 v59, 0x4b800000, v58
	v_cmp_gt_f32_e32 vcc, s84, v58
	s_nop 1
	v_cndmask_b32_e32 v58, v58, v59, vcc
	v_rsq_f32_e32 v58, v58
	s_nop 0
	v_mul_f32_e32 v59, 0x45800000, v58
	v_cndmask_b32_e32 v58, v58, v59, vcc
	v_pk_mul_f32 v[54:55], v[54:55], v[58:59] op_sel_hi:[1,0]
	v_pk_mul_f32 v[50:51], v[50:51], v[58:59] op_sel_hi:[1,0]
	v_pk_mul_f32 v[52:53], v[80:81], v[54:55]
	v_pk_mul_f32 v[50:51], v[78:79], v[50:51]
	v_pk_fma_f32 v[40:41], v[12:13], v[52:53], v[40:41]
	v_pk_fma_f32 v[38:39], v[10:11], v[50:51], v[38:39]
	v_mov_b32_e32 v50, v65
	v_mov_b32_e32 v51, v149
	v_mov_b32_e32 v52, v61
	v_mov_b32_e32 v53, v63
	v_pk_mul_f32 v[50:51], v[50:51], v[58:59] op_sel_hi:[1,0]
	v_pk_mul_f32 v[52:53], v[52:53], v[58:59] op_sel_hi:[1,0]
	v_pk_mul_f32 v[50:51], v[92:93], v[50:51]
	v_pk_mul_f32 v[52:53], v[90:91], v[52:53]
	v_mov_b32_e32 v65, v148
	v_mov_b32_e32 v61, v62
	v_pk_mul_f32 v[152:153], v[152:153], v[58:59] op_sel_hi:[1,0]
	v_pk_mul_f32 v[168:169], v[168:169], v[58:59] op_sel_hi:[1,0]
	v_pk_fma_f32 v[44:45], v[20:21], v[50:51], v[44:45]
	v_pk_fma_f32 v[42:43], v[18:19], v[52:53], v[42:43]
	v_pk_mul_f32 v[50:51], v[64:65], v[58:59] op_sel_hi:[1,0]
	v_pk_mul_f32 v[52:53], v[60:61], v[58:59] op_sel_hi:[1,0]
	v_pk_mul_f32 v[168:169], v[66:67], v[168:169]
	v_pk_mul_f32 v[152:153], v[68:69], v[152:153]
	v_pk_mul_f32 v[52:53], v[110:111], v[52:53]
	v_pk_mul_f32 v[50:51], v[112:113], v[50:51]
	v_pk_fma_f32 v[36:37], v[4:5], v[152:153], v[36:37]
	v_pk_fma_f32 v[34:35], v[2:3], v[168:169], v[34:35]
	v_pk_fma_f32 v[48:49], v[28:29], v[50:51], v[48:49]
	v_pk_fma_f32 v[46:47], v[26:27], v[52:53], v[46:47]
	global_store_dwordx4 v[150:151], v[34:37], off nt
	global_store_dwordx4 v[150:151], v[38:41], off offset:1024 nt
	global_store_dwordx4 v[150:151], v[42:45], off offset:2048 nt
	global_store_dwordx4 v[150:151], v[46:49], off offset:3072 nt
.LBB0_155:
	s_and_b64 vcc, exec, s[40:41]
	s_cbranch_vccnz .LBB0_142
	s_nop 1
	v_mov_b32_e32 v52, v39
	v_mov_b32_e32 v53, v35
	v_mov_b32_e32 v50, v38
	v_mov_b32_e32 v51, v34
	v_pk_mul_f32 v[52:53], v[52:53], v[52:53]
	v_mov_b32_e32 v54, v47
	v_pk_fma_f32 v[50:51], v[50:51], v[50:51], v[52:53]
	v_mov_b32_e32 v52, v40
	v_mov_b32_e32 v53, v36
	v_pk_fma_f32 v[50:51], v[52:53], v[52:53], v[50:51]
	v_mov_b32_e32 v52, v41
	v_mov_b32_e32 v53, v37
	v_mov_b32_e32 v55, v43
	v_pk_fma_f32 v[50:51], v[52:53], v[52:53], v[50:51]
	v_mov_b32_e32 v52, v46
	v_mov_b32_e32 v53, v42
	v_pk_mul_f32 v[54:55], v[54:55], v[54:55]
	v_add_f32_e32 v50, v50, v51
	v_pk_fma_f32 v[52:53], v[52:53], v[52:53], v[54:55]
	v_mov_b32_e32 v54, v48
	v_mov_b32_e32 v55, v44
	v_pk_fma_f32 v[52:53], v[54:55], v[54:55], v[52:53]
	v_mov_b32_e32 v54, v49
	v_mov_b32_e32 v55, v45
	v_pk_fma_f32 v[52:53], v[54:55], v[54:55], v[52:53]
	v_and_b32_e32 v51, 64, v159
	v_add_f32_e32 v50, v53, v50
	v_add_f32_e32 v50, v52, v50
	v_add_u32_e32 v51, 64, v51
	v_xor_b32_e32 v52, 32, v159
	v_cmp_lt_i32_e32 vcc, v52, v51
	s_ashr_i32 s35, s34, 31
	s_lshl_b64 s[20:21], s[34:35], 11
	v_cndmask_b32_e32 v52, v159, v52, vcc
	v_lshlrev_b32_e32 v52, 2, v52
	ds_bpermute_b32 v52, v52, v50
	s_waitcnt lgkmcnt(0)
	v_add_f32_e32 v50, v50, v52
	v_xor_b32_e32 v52, 16, v159
	v_cmp_lt_i32_e32 vcc, v52, v51
	s_nop 1
	v_cndmask_b32_e32 v52, v159, v52, vcc
	v_lshlrev_b32_e32 v52, 2, v52
	ds_bpermute_b32 v52, v52, v50
	s_waitcnt lgkmcnt(0)
	v_add_f32_e32 v50, v50, v52
	v_xor_b32_e32 v52, 8, v159
	v_cmp_lt_i32_e32 vcc, v52, v51
	s_nop 1
	v_cndmask_b32_e32 v52, v159, v52, vcc
	v_lshlrev_b32_e32 v52, 2, v52
	ds_bpermute_b32 v52, v52, v50
	s_waitcnt lgkmcnt(0)
	v_add_f32_e32 v50, v50, v52
	v_xor_b32_e32 v52, 4, v159
	v_cmp_lt_i32_e32 vcc, v52, v51
	s_nop 1
	v_cndmask_b32_e32 v52, v159, v52, vcc
	v_lshlrev_b32_e32 v52, 2, v52
	ds_bpermute_b32 v52, v52, v50
	s_waitcnt lgkmcnt(0)
	v_add_f32_e32 v50, v50, v52
	v_xor_b32_e32 v52, 2, v159
	v_cmp_lt_i32_e32 vcc, v52, v51
	s_nop 1
	v_cndmask_b32_e32 v52, v159, v52, vcc
	v_lshlrev_b32_e32 v52, 2, v52
	ds_bpermute_b32 v52, v52, v50
	s_waitcnt lgkmcnt(0)
	v_add_f32_e32 v50, v50, v52
	v_xor_b32_e32 v52, 1, v159
	v_cmp_lt_i32_e32 vcc, v52, v51
	s_nop 1
	v_cndmask_b32_e32 v51, v159, v52, vcc
	v_lshlrev_b32_e32 v51, 2, v51
	ds_bpermute_b32 v51, v51, v50
	v_lshl_add_u64 v[52:53], v[128:129], 0, s[20:21]
	s_waitcnt lgkmcnt(0)
	v_add_f32_e32 v50, v50, v51
	v_fmamk_f32 v50, v50, 0x3a800000, v155
	v_mul_f32_e32 v51, 0x4b800000, v50
	v_cmp_gt_f32_e32 vcc, s84, v50
	s_nop 1
	v_cndmask_b32_e32 v50, v50, v51, vcc
	v_rsq_f32_e32 v50, v50
	s_nop 0
	v_mul_f32_e32 v51, 0x45800000, v50
	v_cndmask_b32_e32 v50, v50, v51, vcc
	v_pk_mul_f32 v[54:55], v[36:37], v[50:51] op_sel_hi:[1,0]
	v_pk_mul_f32 v[56:57], v[34:35], v[50:51] op_sel_hi:[1,0]
	v_pk_mul_f32 v[54:55], v[8:9], v[54:55]
	v_pk_mul_f32 v[56:57], v[6:7], v[56:57]
	v_pk_fma_f32 v[54:55], v[72:73], v[54:55], v[76:77]
	v_pk_fma_f32 v[56:57], v[70:71], v[56:57], v[74:75]
	s_nop 0
	v_cvt_pk_bf16_f32 v56, v56, v57
	v_cvt_pk_bf16_f32 v57, v54, v55
	v_readlane_b32 vcc_lo, v244, 60
	v_readlane_b32 vcc_hi, v244, 61
	s_nop 3
	v_subrev_u32_e32 v34, vcc_lo, v52
	v_and_b32_e32 v36, 0x7ff, v34
	v_lshrrev_b32_e32 v34, 11, v34
	v_lshlrev_b32_e32 v34, 6, v34
	v_lshrrev_b32_e32 v37, 6, v36
	v_lshl_or_b32 v34, v37, 20, v34
	v_and_or_b32 v34, v36, 63, v34
	v_mov_b32_e32 v35, 0
	v_lshl_add_u64 v[34:35], vcc, 0, v[34:35]
	global_store_dwordx2 v[34:35], v[56:57], off
	v_pk_mul_f32 v[54:55], v[40:41], v[50:51] op_sel_hi:[1,0]
	v_pk_mul_f32 v[56:57], v[38:39], v[50:51] op_sel_hi:[1,0]
	v_pk_mul_f32 v[54:55], v[16:17], v[54:55]
	v_pk_mul_f32 v[56:57], v[14:15], v[56:57]
	v_pk_fma_f32 v[54:55], v[84:85], v[54:55], v[88:89]
	v_pk_fma_f32 v[56:57], v[82:83], v[56:57], v[86:87]
	s_nop 0
	v_cvt_pk_bf16_f32 v56, v56, v57
	v_cvt_pk_bf16_f32 v57, v54, v55
	v_subrev_u32_e32 v34, vcc_lo, v52
	v_add_u32_e32 v34, 0x200, v34
	v_and_b32_e32 v36, 0x7ff, v34
	v_lshrrev_b32_e32 v34, 11, v34
	v_lshlrev_b32_e32 v34, 6, v34
	v_lshrrev_b32_e32 v37, 6, v36
	v_lshl_or_b32 v34, v37, 20, v34
	v_and_or_b32 v34, v36, 63, v34
	v_mov_b32_e32 v35, 0
	v_lshl_add_u64 v[34:35], vcc, 0, v[34:35]
	global_store_dwordx2 v[34:35], v[56:57], off
	v_pk_mul_f32 v[54:55], v[44:45], v[50:51] op_sel_hi:[1,0]
	v_pk_mul_f32 v[56:57], v[42:43], v[50:51] op_sel_hi:[1,0]
	v_pk_mul_f32 v[54:55], v[24:25], v[54:55]
	v_pk_mul_f32 v[56:57], v[22:23], v[56:57]
	v_pk_fma_f32 v[54:55], v[96:97], v[54:55], v[108:109]
	v_pk_fma_f32 v[56:57], v[94:95], v[56:57], v[106:107]
	s_nop 0
	v_cvt_pk_bf16_f32 v56, v56, v57
	v_cvt_pk_bf16_f32 v57, v54, v55
	v_pk_mul_f32 v[54:55], v[48:49], v[50:51] op_sel_hi:[1,0]
	v_pk_mul_f32 v[50:51], v[46:47], v[50:51] op_sel_hi:[1,0]
	v_pk_mul_f32 v[54:55], v[32:33], v[54:55]
	v_pk_mul_f32 v[50:51], v[30:31], v[50:51]
	v_pk_fma_f32 v[54:55], v[116:117], v[54:55], v[120:121]
	v_pk_fma_f32 v[50:51], v[114:115], v[50:51], v[118:119]
	v_subrev_u32_e32 v34, vcc_lo, v52
	v_add_u32_e32 v34, 0x400, v34
	v_and_b32_e32 v36, 0x7ff, v34
	v_lshrrev_b32_e32 v34, 11, v34
	v_lshlrev_b32_e32 v34, 6, v34
	v_lshrrev_b32_e32 v37, 6, v36
	v_lshl_or_b32 v34, v37, 20, v34
	v_and_or_b32 v34, v36, 63, v34
	v_mov_b32_e32 v35, 0
	v_lshl_add_u64 v[34:35], vcc, 0, v[34:35]
	global_store_dwordx2 v[34:35], v[56:57], off
	v_cvt_pk_bf16_f32 v50, v50, v51
	v_cvt_pk_bf16_f32 v51, v54, v55
	v_subrev_u32_e32 v34, vcc_lo, v52
	v_add_u32_e32 v34, 0x600, v34
	v_and_b32_e32 v36, 0x7ff, v34
	v_lshrrev_b32_e32 v34, 11, v34
	v_lshlrev_b32_e32 v34, 6, v34
	v_lshrrev_b32_e32 v37, 6, v36
	v_lshl_or_b32 v34, v37, 20, v34
	v_and_or_b32 v34, v36, 63, v34
	v_mov_b32_e32 v35, 0
	v_lshl_add_u64 v[34:35], vcc, 0, v[34:35]
	global_store_dwordx2 v[34:35], v[50:51], off
	s_branch .LBB0_142

.LBB0_318:
	s_nop 1
	v_lshl_add_u64 v[34:35], s[26:27], 0, v[0:1]
	global_load_dwordx4 v[46:49], v[34:35], off nt
	global_load_dwordx4 v[42:45], v[34:35], off offset:1024 nt
	global_load_dwordx4 v[38:41], v[34:35], off offset:2048 nt
	s_nop 0
	global_load_dwordx4 v[34:37], v[34:35], off offset:3072 nt
	s_add_i32 s7, s6, 1
	s_cmp_ge_i32 s7, s18
	s_cselect_b64 s[34:35], -1, 0
	s_and_b64 vcc, exec, s[34:35]
	s_cbranch_vccnz .LBB0_321
	v_lshl_add_u64 v[18:19], s[30:31], 0, v[0:1]
	global_load_dwordx4 v[30:33], v[18:19], off nt
	global_load_dwordx4 v[26:29], v[18:19], off offset:1024 nt
	global_load_dwordx4 v[22:25], v[18:19], off offset:2048 nt
	s_nop 0
	global_load_dwordx4 v[18:21], v[18:19], off offset:3072 nt
	s_and_b64 vcc, exec, s[38:39]
	s_cbranch_vccz .LBB0_322

.LBB0_323:
	s_nop 1
	v_mov_b32_e32 v36, v27
	v_mov_b32_e32 v37, v31
	v_mov_b32_e32 v34, v26
	v_mov_b32_e32 v35, v30
	v_pk_mul_f32 v[36:37], v[36:37], v[36:37]
	v_mov_b32_e32 v38, v19
	v_pk_fma_f32 v[34:35], v[34:35], v[34:35], v[36:37]
	v_mov_b32_e32 v36, v28
	v_mov_b32_e32 v37, v32
	v_pk_fma_f32 v[34:35], v[36:37], v[36:37], v[34:35]
	v_mov_b32_e32 v36, v29
	v_mov_b32_e32 v37, v33
	v_mov_b32_e32 v39, v23
	v_pk_fma_f32 v[34:35], v[36:37], v[36:37], v[34:35]
	v_mov_b32_e32 v36, v18
	v_mov_b32_e32 v37, v22
	v_pk_mul_f32 v[38:39], v[38:39], v[38:39]
	v_add_f32_e32 v34, v34, v35
	v_pk_fma_f32 v[36:37], v[36:37], v[36:37], v[38:39]
	v_mov_b32_e32 v38, v20
	v_mov_b32_e32 v39, v24
	v_pk_fma_f32 v[36:37], v[38:39], v[38:39], v[36:37]
	v_mov_b32_e32 v38, v21
	v_mov_b32_e32 v39, v25
	v_pk_fma_f32 v[36:37], v[38:39], v[38:39], v[36:37]
	v_and_b32_e32 v35, 64, v159
	v_add_f32_e32 v34, v37, v34
	v_add_f32_e32 v34, v36, v34
	v_add_u32_e32 v35, 64, v35
	v_xor_b32_e32 v36, 32, v159
	v_cmp_lt_i32_e32 vcc, v36, v35
	s_nop 1
	v_cndmask_b32_e32 v36, v159, v36, vcc
	v_lshlrev_b32_e32 v36, 2, v36
	ds_bpermute_b32 v36, v36, v34
	s_waitcnt lgkmcnt(0)
	v_add_f32_e32 v34, v34, v36
	v_xor_b32_e32 v36, 16, v159
	v_cmp_lt_i32_e32 vcc, v36, v35
	s_nop 1
	v_cndmask_b32_e32 v36, v159, v36, vcc
	v_lshlrev_b32_e32 v36, 2, v36
	ds_bpermute_b32 v36, v36, v34
	s_waitcnt lgkmcnt(0)
	v_add_f32_e32 v34, v34, v36
	v_xor_b32_e32 v36, 8, v159
	v_cmp_lt_i32_e32 vcc, v36, v35
	s_nop 1
	v_cndmask_b32_e32 v36, v159, v36, vcc
	v_lshlrev_b32_e32 v36, 2, v36
	ds_bpermute_b32 v36, v36, v34
	s_waitcnt lgkmcnt(0)
	v_add_f32_e32 v34, v34, v36
	v_xor_b32_e32 v36, 4, v159
	v_cmp_lt_i32_e32 vcc, v36, v35
	s_nop 1
	v_cndmask_b32_e32 v36, v159, v36, vcc
	v_lshlrev_b32_e32 v36, 2, v36
	ds_bpermute_b32 v36, v36, v34
	s_waitcnt lgkmcnt(0)
	v_add_f32_e32 v34, v34, v36
	v_xor_b32_e32 v36, 2, v159
	v_cmp_lt_i32_e32 vcc, v36, v35
	s_nop 1
	v_cndmask_b32_e32 v36, v159, v36, vcc
	v_lshlrev_b32_e32 v36, 2, v36
	ds_bpermute_b32 v36, v36, v34
	s_waitcnt lgkmcnt(0)
	v_add_f32_e32 v34, v34, v36
	v_xor_b32_e32 v36, 1, v159
	v_cmp_lt_i32_e32 vcc, v36, v35
	s_nop 1
	v_cndmask_b32_e32 v35, v159, v36, vcc
	v_lshlrev_b32_e32 v35, 2, v35
	ds_bpermute_b32 v35, v35, v34
	v_lshl_add_u64 v[36:37], s[28:29], 0, v[82:83]
	s_waitcnt lgkmcnt(0)
	v_add_f32_e32 v34, v34, v35
	v_fmamk_f32 v34, v34, 0x3a800000, v155
	v_mul_f32_e32 v35, 0x4b800000, v34
	v_cmp_gt_f32_e32 vcc, s84, v34
	s_nop 1
	v_cndmask_b32_e32 v34, v34, v35, vcc
	v_rsq_f32_e32 v34, v34
	s_nop 0
	v_mul_f32_e32 v35, 0x45800000, v34
	v_cndmask_b32_e32 v34, v34, v35, vcc
	v_pk_mul_f32 v[38:39], v[32:33], v[34:35] op_sel_hi:[1,0]
	v_pk_mul_f32 v[40:41], v[30:31], v[34:35] op_sel_hi:[1,0]
	v_pk_mul_f32 v[38:39], v[4:5], v[38:39]
	v_pk_mul_f32 v[40:41], v[2:3], v[40:41]
	v_pk_fma_f32 v[38:39], v[52:53], v[38:39], v[56:57]
	v_pk_fma_f32 v[40:41], v[50:51], v[40:41], v[54:55]
	s_nop 0
	v_cvt_pk_bf16_f32 v40, v40, v41
	v_cvt_pk_bf16_f32 v41, v38, v39
	v_readlane_b32 vcc_lo, v244, 60
	v_readlane_b32 vcc_hi, v244, 61
	s_nop 3
	v_subrev_u32_e32 v30, vcc_lo, v36
	v_and_b32_e32 v32, 0x7ff, v30
	v_lshrrev_b32_e32 v30, 11, v30
	v_lshlrev_b32_e32 v30, 6, v30
	v_lshrrev_b32_e32 v33, 6, v32
	v_lshl_or_b32 v30, v33, 20, v30
	v_and_or_b32 v30, v32, 63, v30
	v_mov_b32_e32 v31, 0
	v_lshl_add_u64 v[30:31], vcc, 0, v[30:31]
	global_store_dwordx2 v[30:31], v[40:41], off
	v_pk_mul_f32 v[38:39], v[28:29], v[34:35] op_sel_hi:[1,0]
	v_pk_mul_f32 v[40:41], v[26:27], v[34:35] op_sel_hi:[1,0]
	v_pk_mul_f32 v[38:39], v[8:9], v[38:39]
	v_pk_mul_f32 v[40:41], v[6:7], v[40:41]
	v_pk_fma_f32 v[38:39], v[60:61], v[38:39], v[64:65]
	v_pk_fma_f32 v[40:41], v[58:59], v[40:41], v[62:63]
	s_nop 0
	v_cvt_pk_bf16_f32 v40, v40, v41
	v_cvt_pk_bf16_f32 v41, v38, v39
	v_subrev_u32_e32 v30, vcc_lo, v36
	v_add_u32_e32 v30, 0x200, v30
	v_and_b32_e32 v32, 0x7ff, v30
	v_lshrrev_b32_e32 v30, 11, v30
	v_lshlrev_b32_e32 v30, 6, v30
	v_lshrrev_b32_e32 v33, 6, v32
	v_lshl_or_b32 v30, v33, 20, v30
	v_and_or_b32 v30, v32, 63, v30
	v_mov_b32_e32 v31, 0
	v_lshl_add_u64 v[30:31], vcc, 0, v[30:31]
	global_store_dwordx2 v[30:31], v[40:41], off
	v_pk_mul_f32 v[38:39], v[24:25], v[34:35] op_sel_hi:[1,0]
	v_pk_mul_f32 v[40:41], v[22:23], v[34:35] op_sel_hi:[1,0]
	v_pk_mul_f32 v[38:39], v[12:13], v[38:39]
	v_pk_mul_f32 v[40:41], v[10:11], v[40:41]
	v_pk_fma_f32 v[38:39], v[68:69], v[38:39], v[72:73]
	v_pk_fma_f32 v[40:41], v[66:67], v[40:41], v[70:71]
	s_nop 0
	v_cvt_pk_bf16_f32 v40, v40, v41
	v_cvt_pk_bf16_f32 v41, v38, v39
	v_pk_mul_f32 v[38:39], v[20:21], v[34:35] op_sel_hi:[1,0]
	v_pk_mul_f32 v[34:35], v[18:19], v[34:35] op_sel_hi:[1,0]
	v_pk_mul_f32 v[38:39], v[16:17], v[38:39]
	v_pk_mul_f32 v[34:35], v[14:15], v[34:35]
	v_pk_fma_f32 v[38:39], v[76:77], v[38:39], v[80:81]
	v_pk_fma_f32 v[34:35], v[74:75], v[34:35], v[78:79]
	v_subrev_u32_e32 v30, vcc_lo, v36
	v_add_u32_e32 v30, 0x400, v30
	v_and_b32_e32 v32, 0x7ff, v30
	v_lshrrev_b32_e32 v30, 11, v30
	v_lshlrev_b32_e32 v30, 6, v30
	v_lshrrev_b32_e32 v33, 6, v32
	v_lshl_or_b32 v30, v33, 20, v30
	v_and_or_b32 v30, v32, 63, v30
	v_mov_b32_e32 v31, 0
	v_lshl_add_u64 v[30:31], vcc, 0, v[30:31]
	global_store_dwordx2 v[30:31], v[40:41], off
	v_cvt_pk_bf16_f32 v34, v34, v35
	v_cvt_pk_bf16_f32 v35, v38, v39
	v_subrev_u32_e32 v30, vcc_lo, v36
	v_add_u32_e32 v30, 0x600, v30
	v_and_b32_e32 v32, 0x7ff, v30
	v_lshrrev_b32_e32 v30, 11, v30
	v_lshlrev_b32_e32 v30, 6, v30
	v_lshrrev_b32_e32 v33, 6, v32
	v_lshl_or_b32 v30, v33, 20, v30
	v_and_or_b32 v30, v32, 63, v30
	v_mov_b32_e32 v31, 0
	v_lshl_add_u64 v[30:31], vcc, 0, v[30:31]
	global_store_dwordx2 v[30:31], v[34:35], off
	s_branch .LBB0_317

.LBB0_535:
	s_add_i32 s26, s6, 1
	s_cmp_lt_i32 s26, s18
	s_cselect_b64 s[28:29], -1, 0
	s_cmp_ge_i32 s26, s18
	s_cbranch_scc1 .LBB0_538
	s_ashr_i32 s27, s26, 31
	s_lshl_b64 s[20:21], s[26:27], 12
	s_nop 1
	v_lshl_add_u64 v[18:19], v[66:67], 0, s[20:21]
	global_load_dwordx4 v[30:33], v[18:19], off nt
	global_load_dwordx4 v[26:29], v[18:19], off offset:1024 nt
	global_load_dwordx4 v[22:25], v[18:19], off offset:2048 nt
	s_nop 0
	global_load_dwordx4 v[18:21], v[18:19], off offset:3072 nt
	s_and_b64 vcc, exec, s[38:39]
	s_cbranch_vccnz .LBB0_538
	s_lshl_b64 s[20:21], s[26:27], 11
	v_lshl_add_u64 v[74:75], v[68:69], 0, s[20:21]
	global_load_dwordx2 v[80:81], v[74:75], off nt
	global_load_dwordx2 v[78:79], v[74:75], off offset:512 nt
	global_load_dwordx2 v[76:77], v[74:75], off offset:1024 nt
	s_nop 0
	global_load_dwordx2 v[74:75], v[74:75], off offset:1536 nt

.LBB0_540:
	s_andn2_b64 vcc, exec, s[28:29]
	s_cbranch_vccnz .LBB0_532
	s_and_b64 vcc, exec, s[38:39]
	s_cbranch_vccnz .LBB0_532
	s_nop 1
	v_and_b32_e32 v37, 0xffff0000, v80
	v_and_b32_e32 v36, 0xffff0000, v78
	v_lshlrev_b32_e32 v35, 16, v80
	v_lshlrev_b32_e32 v34, 16, v78
	v_pk_mul_f32 v[42:43], v[36:37], v[36:37]
	v_lshlrev_b32_e32 v39, 16, v81
	v_lshlrev_b32_e32 v38, 16, v79
	v_pk_fma_f32 v[42:43], v[34:35], v[34:35], v[42:43]
	v_and_b32_e32 v41, 0xffff0000, v81
	v_and_b32_e32 v40, 0xffff0000, v79
	v_pk_fma_f32 v[42:43], v[38:39], v[38:39], v[42:43]
	v_and_b32_e32 v47, 0xffff0000, v76
	v_and_b32_e32 v46, 0xffff0000, v74
	v_pk_fma_f32 v[42:43], v[40:41], v[40:41], v[42:43]
	v_lshlrev_b32_e32 v45, 16, v76
	v_lshlrev_b32_e32 v44, 16, v74
	v_pk_mul_f32 v[92:93], v[46:47], v[46:47]
	v_lshlrev_b32_e32 v49, 16, v77
	v_lshlrev_b32_e32 v48, 16, v75
	v_pk_fma_f32 v[92:93], v[44:45], v[44:45], v[92:93]
	v_add_f32_e32 v0, v42, v43
	v_and_b32_e32 v42, 64, v159
	v_and_b32_e32 v91, 0xffff0000, v77
	v_and_b32_e32 v90, 0xffff0000, v75
	v_pk_fma_f32 v[92:93], v[48:49], v[48:49], v[92:93]
	v_add_u32_e32 v42, 64, v42
	v_xor_b32_e32 v43, 32, v159
	v_pk_fma_f32 v[92:93], v[90:91], v[90:91], v[92:93]
	v_cmp_lt_i32_e32 vcc, v43, v42
	v_add_f32_e32 v0, v93, v0
	v_add_f32_e32 v0, v92, v0
	v_cndmask_b32_e32 v43, v159, v43, vcc
	v_lshlrev_b32_e32 v43, 2, v43
	ds_bpermute_b32 v43, v43, v0
	v_mov_b32_e32 v92, v39
	v_mov_b32_e32 v94, v35
	v_mov_b32_e32 v39, v40
	v_mov_b32_e32 v35, v36
	s_waitcnt lgkmcnt(0)
	v_add_f32_e32 v0, v0, v43
	v_xor_b32_e32 v43, 16, v159
	v_cmp_lt_i32_e32 vcc, v43, v42
	v_mov_b32_e32 v95, v37
	v_mov_b32_e32 v93, v41
	v_cndmask_b32_e32 v43, v159, v43, vcc
	v_lshlrev_b32_e32 v43, 2, v43
	ds_bpermute_b32 v43, v43, v0
	s_ashr_i32 s27, s26, 31
	s_lshl_b64 s[20:21], s[26:27], 12
	s_waitcnt lgkmcnt(0)
	v_add_f32_e32 v0, v0, v43
	v_xor_b32_e32 v43, 8, v159
	v_cmp_lt_i32_e32 vcc, v43, v42
	s_nop 1
	v_cndmask_b32_e32 v43, v159, v43, vcc
	v_lshlrev_b32_e32 v43, 2, v43
	ds_bpermute_b32 v43, v43, v0
	s_waitcnt lgkmcnt(0)
	v_add_f32_e32 v0, v0, v43
	v_xor_b32_e32 v43, 4, v159
	v_cmp_lt_i32_e32 vcc, v43, v42
	s_nop 1
	v_cndmask_b32_e32 v43, v159, v43, vcc
	v_lshlrev_b32_e32 v43, 2, v43
	ds_bpermute_b32 v43, v43, v0
	s_waitcnt lgkmcnt(0)
	v_add_f32_e32 v0, v0, v43
	v_xor_b32_e32 v43, 2, v159
	v_cmp_lt_i32_e32 vcc, v43, v42
	s_nop 1
	v_cndmask_b32_e32 v43, v159, v43, vcc
	v_lshlrev_b32_e32 v43, 2, v43
	ds_bpermute_b32 v43, v43, v0
	s_waitcnt lgkmcnt(0)
	v_add_f32_e32 v0, v0, v43
	v_xor_b32_e32 v43, 1, v159
	v_cmp_lt_i32_e32 vcc, v43, v42
	s_nop 1
	v_cndmask_b32_e32 v42, v159, v43, vcc
	v_lshlrev_b32_e32 v42, 2, v42
	ds_bpermute_b32 v42, v42, v0
	s_waitcnt lgkmcnt(0)
	v_add_f32_e32 v0, v0, v42
	v_fmamk_f32 v0, v0, 0x3a800000, v155
	v_mul_f32_e32 v42, 0x4b800000, v0
	v_cmp_gt_f32_e32 vcc, s84, v0
	s_nop 1
	v_cndmask_b32_e32 v0, v0, v42, vcc
	v_rsq_f32_e32 v0, v0
	s_nop 0
	v_mul_f32_e32 v42, 0x45800000, v0
	v_cndmask_b32_e32 v0, v0, v42, vcc
	v_pk_mul_f32 v[38:39], v[38:39], v[0:1] op_sel_hi:[1,0]
	v_pk_mul_f32 v[34:35], v[34:35], v[0:1] op_sel_hi:[1,0]
	v_pk_mul_f32 v[36:37], v[56:57], v[38:39]
	v_pk_mul_f32 v[34:35], v[54:55], v[34:35]
	v_pk_fma_f32 v[28:29], v[8:9], v[36:37], v[28:29]
	v_pk_fma_f32 v[26:27], v[6:7], v[34:35], v[26:27]
	v_mov_b32_e32 v34, v49
	v_mov_b32_e32 v35, v91
	v_mov_b32_e32 v36, v45
	v_mov_b32_e32 v37, v47
	v_pk_mul_f32 v[34:35], v[34:35], v[0:1] op_sel_hi:[1,0]
	v_pk_mul_f32 v[36:37], v[36:37], v[0:1] op_sel_hi:[1,0]
	v_pk_mul_f32 v[34:35], v[60:61], v[34:35]
	v_pk_mul_f32 v[36:37], v[58:59], v[36:37]
	v_mov_b32_e32 v49, v90
	v_mov_b32_e32 v45, v46
	v_pk_mul_f32 v[92:93], v[92:93], v[0:1] op_sel_hi:[1,0]
	v_pk_mul_f32 v[94:95], v[94:95], v[0:1] op_sel_hi:[1,0]
	v_pk_fma_f32 v[24:25], v[12:13], v[34:35], v[24:25]
	v_pk_fma_f32 v[22:23], v[10:11], v[36:37], v[22:23]
	v_pk_mul_f32 v[34:35], v[48:49], v[0:1] op_sel_hi:[1,0]
	v_pk_mul_f32 v[36:37], v[44:45], v[0:1] op_sel_hi:[1,0]
	v_pk_mul_f32 v[94:95], v[50:51], v[94:95]
	v_pk_mul_f32 v[92:93], v[52:53], v[92:93]
	v_pk_mul_f32 v[36:37], v[62:63], v[36:37]
	v_pk_mul_f32 v[34:35], v[64:65], v[34:35]
	v_lshl_add_u64 v[42:43], v[66:67], 0, s[20:21]
	v_pk_fma_f32 v[32:33], v[4:5], v[92:93], v[32:33]
	v_pk_fma_f32 v[30:31], v[2:3], v[94:95], v[30:31]
	v_pk_fma_f32 v[20:21], v[16:17], v[34:35], v[20:21]
	v_pk_fma_f32 v[18:19], v[14:15], v[36:37], v[18:19]
	global_store_dwordx4 v[42:43], v[30:33], off nt
	global_store_dwordx4 v[42:43], v[26:29], off offset:1024 nt
	global_store_dwordx4 v[42:43], v[22:25], off offset:2048 nt
	global_store_dwordx4 v[42:43], v[18:21], off offset:3072 nt
	s_branch .LBB0_532
